# stick-breaking loop: V fragment LDS reads issued with the K reads (spare VGPRs)
# speedup vs baseline: 1.0093x; 1.0036x over previous
; #define LAS __attribute__((address_space(3)))
; #define MFMA32(a, b, c) __builtin_amdgcn_mfma_f32_32x32x16_bf16((a), (b), (c), 0, 0, 0)
; DI s16x4 vtr(LAS const char* p) { return __builtin_bit_cast(s16x4, __builtin_amdgcn_ds_read_tr16_b64_v4i16((LAS v4i16_t*)p)); }
; template <int KS0, int KS1> DI f32x16 qk_rows(LAS const char* Kl, int row0, const bf16x8 (&qf)[4], int r, int h) {
;     f32x16 s;
; #pragma unroll
;     for (int i = 0; i < 16; ++i) s[i] = 0.f;
;     LAS const char* p = Kl + (row0 + r) * KP + 16 * h;
;     bf16x8 kf[4];
; #pragma unroll
;     for (int ks = KS0; ks < KS1; ++ks) kf[ks] = *(LAS const bf16x8*)(p + 32 * ks);
;     __builtin_amdgcn_s_setprio(1);
; #pragma unroll
;     for (int ks = KS0; ks < KS1; ++ks) s = MFMA32(kf[ks], qf[ks], s);
;     __builtin_amdgcn_s_setprio(0);
;     return s;
; }
; DI void pv_rows(f32x16 (&o)[2], LAS const char* Vl, int row0, const bf16x8 (&pf)[2], int lane) {
;     const int h = lane >> 5, i = lane & 15, grp = (lane >> 4) & 1;
;     LAS const char* base = Vl + (row0 + 4 * h + (i >> 2)) * KP + grp * 32 + (i & 3) * 8;
;     bf16x8 vf[2][2];
; #pragma unroll
;     for (int dt = 0; dt < 2; ++dt)
; #pragma unroll
;         for (int s2 = 0; s2 < 2; ++s2) {
;             const s16x4 lo = vtr(base + (16 * s2) * KP + dt * 64), hi = vtr(base + (16 * s2 + 8) * KP + dt * 64);
;             vf[dt][s2] = (bf16x8){lo[0], lo[1], lo[2], lo[3], hi[0], hi[1], hi[2], hi[3]};
;         }
; DI void sb_unit(const Params& P, LAS char* lds, int b, int hd, int qb, int wave, int lane) {
;     ...
;         const f32x16 s = qk_rows<0, 4>(Kl, 0, qf, r, h);
;         float l1m[16], ls[16];
;         unsigned vm = 0;
; #pragma unroll
;         for (int i = 0; i < 16; ++i) { const int kidx = kbase + (i & 3) + 8 * (i >> 2) + 4 * h; const bool ok = kidx < qpos; vm |= ok ? (1u << i) : 0u;
;             const float z = s[i] * 0.125f; const float sp = fmaxf(z, 0.f) + __logf(1.0f + __expf(-fabsf(z)));
;             l1m[i] = ok ? -sp : 0.f; ls[i] = z - sp; }
.Lsb_nopf:
	s_waitcnt lgkmcnt(0)
	ds_read_b128 v[32:35], v105
	ds_read_b128 v[64:67], v105 offset:32
	ds_read_b128 v[68:71], v105 offset:64
	ds_read_b128 v[76:79], v105 offset:96
	ds_read_b64_tr_b16 v[116:117], v106 offset:4608
	ds_read_b64_tr_b16 v[118:119], v106 offset:5760
	ds_read_b64_tr_b16 v[120:121], v106 offset:4672
	ds_read_b64_tr_b16 v[122:123], v106 offset:5824
	ds_read_b64_tr_b16 v[124:125], v106 offset:6912
	ds_read_b64_tr_b16 v[126:127], v106 offset:8064
	ds_read_b64_tr_b16 v[160:161], v106 offset:6976
	ds_read_b64_tr_b16 v[162:163], v106 offset:8128
	s_setprio 1
	s_waitcnt lgkmcnt(11)
	v_mfma_f32_32x32x16_bf16 v[32:47], v[32:35], v[48:51], 0
	s_waitcnt lgkmcnt(10)
	v_mfma_f32_32x32x16_bf16 v[32:47], v[64:67], v[52:55], v[32:47]
	s_waitcnt lgkmcnt(9)
	v_mfma_f32_32x32x16_bf16 v[32:47], v[68:71], v[56:59], v[32:47]
	s_waitcnt lgkmcnt(8)
	v_mfma_f32_32x32x16_bf16 v[32:47], v[76:79], v[60:63], v[32:47]
	s_setprio 0
	s_nop 10
	v_mul_f32_e32 v64, 0x3e000000, v32
	v_max_f32_e32 v65, 0, v64
	v_mul_f32_e64 v64, |v64|, s17
	v_exp_f32_e32 v64, v64
	v_mul_f32_e32 v70, 0x3e000000, v45
	v_mul_f32_e32 v78, 0x3e000000, v46
	v_mul_f32_e32 v82, 0x3e000000, v47
	v_add_f32_e32 v64, 1.0, v64
	v_cmp_gt_f32_e32 vcc, s21, v64
	s_nop 1
	v_cndmask_b32_e64 v66, 0, 32, vcc
	v_ldexp_f32 v64, v64, v66
	v_log_f32_e32 v64, v64
	s_nop 0
	v_mul_f32_e32 v66, 0x3f317217, v64
	v_fma_f32 v66, v64, s30, -v66
	v_fmac_f32_e32 v66, 0x3377d1cf, v64
	v_fmac_f32_e32 v66, 0x3f317217, v64
	v_cmp_lt_f32_e64 s[0:1], |v64|, s19
	s_nop 1
	v_cndmask_b32_e64 v64, v64, v66, s[0:1]
	v_cndmask_b32_e32 v66, 0, v211, vcc
	v_sub_f32_e32 v67, v64, v66
	v_mul_f32_e32 v64, 0x3e000000, v33
	v_max_f32_e32 v69, 0, v64
	v_mul_f32_e64 v64, |v64|, s17
	v_exp_f32_e32 v64, v64
	s_nop 0
	v_add_f32_e32 v64, 1.0, v64
	v_cmp_gt_f32_e32 vcc, s21, v64
	s_nop 1
	v_cndmask_b32_e64 v66, 0, 32, vcc
	v_ldexp_f32 v64, v64, v66
	v_log_f32_e32 v64, v64
	s_nop 0
	v_mul_f32_e32 v66, 0x3f317217, v64
	v_fma_f32 v66, v64, s30, -v66
	v_fmac_f32_e32 v66, 0x3377d1cf, v64
	v_fmac_f32_e32 v66, 0x3f317217, v64
	v_cmp_lt_f32_e64 s[0:1], |v64|, s19
	s_nop 1
	v_cndmask_b32_e64 v64, v64, v66, s[0:1]
	v_cndmask_b32_e32 v66, 0, v211, vcc
	v_sub_f32_e32 v71, v64, v66
	v_mul_f32_e32 v64, 0x3e000000, v34
	v_max_f32_e32 v77, 0, v64
	v_mul_f32_e64 v64, |v64|, s17
	v_exp_f32_e32 v64, v64
	s_nop 0
	v_add_f32_e32 v64, 1.0, v64
	v_cmp_gt_f32_e32 vcc, s21, v64
	s_nop 1
	v_cndmask_b32_e64 v66, 0, 32, vcc
	v_ldexp_f32 v64, v64, v66
	v_log_f32_e32 v64, v64
	s_nop 0
	v_mul_f32_e32 v66, 0x3f317217, v64
	v_fma_f32 v66, v64, s30, -v66
	v_fmac_f32_e32 v66, 0x3377d1cf, v64
	v_fmac_f32_e32 v66, 0x3f317217, v64
	v_cmp_lt_f32_e64 s[0:1], |v64|, s19
	s_nop 1
	v_cndmask_b32_e64 v64, v64, v66, s[0:1]
	v_cndmask_b32_e32 v66, 0, v211, vcc
	v_sub_f32_e32 v79, v64, v66
	v_mul_f32_e32 v64, 0x3e000000, v35
	v_max_f32_e32 v81, 0, v64
	v_mul_f32_e64 v64, |v64|, s17
	v_exp_f32_e32 v64, v64
	s_nop 0
	v_add_f32_e32 v64, 1.0, v64
	v_cmp_gt_f32_e32 vcc, s21, v64
	s_nop 1
	v_cndmask_b32_e64 v66, 0, 32, vcc
	v_ldexp_f32 v64, v64, v66
	v_log_f32_e32 v64, v64
	s_nop 0
	v_mul_f32_e32 v66, 0x3f317217, v64
	v_fma_f32 v66, v64, s30, -v66
	v_fmac_f32_e32 v66, 0x3377d1cf, v64
	v_fmac_f32_e32 v66, 0x3f317217, v64
	v_cmp_lt_f32_e64 s[0:1], |v64|, s19
	s_nop 1
	v_cndmask_b32_e64 v64, v64, v66, s[0:1]
	v_cndmask_b32_e32 v66, 0, v211, vcc
	v_sub_f32_e32 v83, v64, v66
	v_mul_f32_e32 v64, 0x3e000000, v36
	v_max_f32_e32 v85, 0, v64
	v_mul_f32_e64 v64, |v64|, s17
	v_exp_f32_e32 v64, v64
	s_nop 0
	v_add_f32_e32 v64, 1.0, v64
	v_cmp_gt_f32_e32 vcc, s21, v64
	s_nop 1
	v_cndmask_b32_e64 v66, 0, 32, vcc
	v_ldexp_f32 v64, v64, v66
	v_log_f32_e32 v64, v64
	s_nop 0
	v_mul_f32_e32 v66, 0x3f317217, v64
	v_fma_f32 v66, v64, s30, -v66
	v_fmac_f32_e32 v66, 0x3377d1cf, v64
	v_fmac_f32_e32 v66, 0x3f317217, v64
	v_cmp_lt_f32_e64 s[0:1], |v64|, s19
	s_nop 1
	v_cndmask_b32_e64 v64, v64, v66, s[0:1]
	v_cndmask_b32_e32 v66, 0, v211, vcc
	v_sub_f32_e32 v87, v64, v66
	v_mul_f32_e32 v64, 0x3e000000, v37
	v_max_f32_e32 v89, 0, v64
	v_mul_f32_e64 v64, |v64|, s17
	v_exp_f32_e32 v64, v64
	s_nop 0
	v_add_f32_e32 v64, 1.0, v64
	v_cmp_gt_f32_e32 vcc, s21, v64
	s_nop 1
	v_cndmask_b32_e64 v66, 0, 32, vcc
	v_ldexp_f32 v64, v64, v66
	v_log_f32_e32 v64, v64
	s_nop 0
	v_mul_f32_e32 v66, 0x3f317217, v64
	v_fma_f32 v66, v64, s30, -v66
	v_fmac_f32_e32 v66, 0x3377d1cf, v64
	v_fmac_f32_e32 v66, 0x3f317217, v64
	v_cmp_lt_f32_e64 s[0:1], |v64|, s19
	s_nop 1
	v_cndmask_b32_e64 v64, v64, v66, s[0:1]
	v_cndmask_b32_e32 v66, 0, v211, vcc
	v_sub_f32_e32 v91, v64, v66
	v_mul_f32_e32 v64, 0x3e000000, v38
	v_max_f32_e32 v93, 0, v64
	v_mul_f32_e64 v64, |v64|, s17
	v_exp_f32_e32 v64, v64
	s_nop 0
	v_add_f32_e32 v64, 1.0, v64
	v_cmp_gt_f32_e32 vcc, s21, v64
	s_nop 1
	v_cndmask_b32_e64 v66, 0, 32, vcc
	v_ldexp_f32 v64, v64, v66
	v_log_f32_e32 v64, v64
	s_nop 0
	v_mul_f32_e32 v66, 0x3f317217, v64
	v_fma_f32 v66, v64, s30, -v66
	v_fmac_f32_e32 v66, 0x3377d1cf, v64
	v_fmac_f32_e32 v66, 0x3f317217, v64
	v_cmp_lt_f32_e64 s[0:1], |v64|, s19
	s_nop 1
	v_cndmask_b32_e64 v64, v64, v66, s[0:1]
	v_cndmask_b32_e32 v66, 0, v211, vcc
	v_sub_f32_e32 v95, v64, v66
	v_mul_f32_e32 v64, 0x3e000000, v39
	v_max_f32_e32 v97, 0, v64
	v_mul_f32_e64 v64, |v64|, s17
	v_exp_f32_e32 v64, v64
	s_nop 0
	v_add_f32_e32 v64, 1.0, v64
	v_cmp_gt_f32_e32 vcc, s21, v64
	s_nop 1
	v_cndmask_b32_e64 v66, 0, 32, vcc
	v_ldexp_f32 v64, v64, v66
	v_log_f32_e32 v64, v64
	s_nop 0
	v_mul_f32_e32 v66, 0x3f317217, v64
	v_fma_f32 v66, v64, s30, -v66
	v_fmac_f32_e32 v66, 0x3377d1cf, v64
	v_fmac_f32_e32 v66, 0x3f317217, v64
	v_cmp_lt_f32_e64 s[0:1], |v64|, s19
	s_nop 1
; DI void sb_unit(const Params& P, LAS char* lds, int b, int hd, int qb, int wave, int lane) {
;     ...
;         for (int i = 0; i < 16; ++i) { const int kidx = kbase + (i & 3) + 8 * (i >> 2) + 4 * h; const bool ok = kidx < qpos; vm |= ok ? (1u << i) : 0u;
;             const float z = s[i] * 0.125f; const float sp = fmaxf(z, 0.f) + __logf(1.0f + __expf(-fabsf(z)));
;             l1m[i] = ok ? -sp : 0.f; ls[i] = z - sp; }
	v_cndmask_b32_e64 v64, v64, v66, s[0:1]
	v_cndmask_b32_e32 v66, 0, v211, vcc
	v_sub_f32_e32 v99, v64, v66
	v_mul_f32_e32 v64, 0x3e000000, v40
	v_max_f32_e32 v84, 0, v64
	v_mul_f32_e64 v64, |v64|, s17
	v_exp_f32_e32 v64, v64
	s_nop 0
	v_add_f32_e32 v64, 1.0, v64
	v_cmp_gt_f32_e32 vcc, s21, v64
	s_nop 1
	v_cndmask_b32_e64 v66, 0, 32, vcc
	v_ldexp_f32 v64, v64, v66
	v_log_f32_e32 v64, v64
	s_nop 0
	v_mul_f32_e32 v66, 0x3f317217, v64
	v_fma_f32 v66, v64, s30, -v66
	v_fmac_f32_e32 v66, 0x3377d1cf, v64
	v_fmac_f32_e32 v66, 0x3f317217, v64
	v_cmp_lt_f32_e64 s[0:1], |v64|, s19
	s_nop 1
	v_cndmask_b32_e64 v64, v64, v66, s[0:1]
	v_cndmask_b32_e32 v66, 0, v211, vcc
	v_sub_f32_e32 v86, v64, v66
	v_mul_f32_e32 v64, 0x3e000000, v41
	v_max_f32_e32 v88, 0, v64
	v_mul_f32_e64 v64, |v64|, s17
	v_exp_f32_e32 v64, v64
	s_nop 0
	v_add_f32_e32 v64, 1.0, v64
	v_cmp_gt_f32_e32 vcc, s21, v64
	s_nop 1
	v_cndmask_b32_e64 v66, 0, 32, vcc
	v_ldexp_f32 v64, v64, v66
	v_log_f32_e32 v64, v64
	s_nop 0
	v_mul_f32_e32 v66, 0x3f317217, v64
	v_fma_f32 v66, v64, s30, -v66
	v_fmac_f32_e32 v66, 0x3377d1cf, v64
	v_fmac_f32_e32 v66, 0x3f317217, v64
	v_cmp_lt_f32_e64 s[0:1], |v64|, s19
	s_nop 1
	v_cndmask_b32_e64 v64, v64, v66, s[0:1]
	v_cndmask_b32_e32 v66, 0, v211, vcc
	v_sub_f32_e32 v90, v64, v66
	v_mul_f32_e32 v64, 0x3e000000, v42
	v_max_f32_e32 v92, 0, v64
	v_mul_f32_e64 v64, |v64|, s17
	v_exp_f32_e32 v64, v64
	s_nop 0
	v_add_f32_e32 v64, 1.0, v64
	v_cmp_gt_f32_e32 vcc, s21, v64
	s_nop 1
	v_cndmask_b32_e64 v66, 0, 32, vcc
	v_ldexp_f32 v64, v64, v66
	v_log_f32_e32 v64, v64
	s_nop 0
	v_mul_f32_e32 v66, 0x3f317217, v64
	v_fma_f32 v66, v64, s30, -v66
	v_fmac_f32_e32 v66, 0x3377d1cf, v64
	v_fmac_f32_e32 v66, 0x3f317217, v64
	v_cmp_lt_f32_e64 s[0:1], |v64|, s19
	s_nop 1
	v_cndmask_b32_e64 v64, v64, v66, s[0:1]
	v_cndmask_b32_e32 v66, 0, v211, vcc
	v_sub_f32_e32 v94, v64, v66
	v_mul_f32_e32 v64, 0x3e000000, v43
	v_max_f32_e32 v96, 0, v64
	v_mul_f32_e64 v64, |v64|, s17
	v_exp_f32_e32 v64, v64
	s_nop 0
	v_add_f32_e32 v64, 1.0, v64
	v_cmp_gt_f32_e32 vcc, s21, v64
	s_nop 1
	v_cndmask_b32_e64 v66, 0, 32, vcc
	v_ldexp_f32 v64, v64, v66
	v_log_f32_e32 v64, v64
	s_nop 0
	v_mul_f32_e32 v66, 0x3f317217, v64
	v_fma_f32 v66, v64, s30, -v66
	v_fmac_f32_e32 v66, 0x3377d1cf, v64
	v_fmac_f32_e32 v66, 0x3f317217, v64
	v_cmp_lt_f32_e64 s[0:1], |v64|, s19
	s_nop 1
	v_cndmask_b32_e64 v64, v64, v66, s[0:1]
	v_cndmask_b32_e32 v66, 0, v211, vcc
	v_sub_f32_e32 v98, v64, v66
	v_mul_f32_e32 v66, 0x3e000000, v44
	v_max_f32_e32 v64, 0, v66
	v_mul_f32_e64 v66, |v66|, s17
	v_exp_f32_e32 v66, v66
	s_nop 0
	v_add_f32_e32 v66, 1.0, v66
	v_cmp_gt_f32_e32 vcc, s21, v66
	s_nop 1
	v_cndmask_b32_e64 v68, 0, 32, vcc
	v_ldexp_f32 v66, v66, v68
	v_log_f32_e32 v66, v66
	s_nop 0
	v_mul_f32_e32 v68, 0x3f317217, v66
	v_fma_f32 v68, v66, s30, -v68
	v_fmac_f32_e32 v68, 0x3377d1cf, v66
	v_fmac_f32_e32 v68, 0x3f317217, v66
	v_cmp_lt_f32_e64 s[0:1], |v66|, s19
	s_nop 1
	v_cndmask_b32_e64 v66, v66, v68, s[0:1]
	v_cndmask_b32_e32 v68, 0, v211, vcc
	v_sub_f32_e32 v66, v66, v68
	v_max_f32_e32 v68, 0, v70
	v_mul_f32_e64 v70, |v70|, s17
	v_exp_f32_e32 v70, v70
	s_nop 0
	v_add_f32_e32 v70, 1.0, v70
	v_cmp_gt_f32_e32 vcc, s21, v70
	s_nop 1
	v_cndmask_b32_e64 v76, 0, 32, vcc
	v_ldexp_f32 v70, v70, v76
	v_log_f32_e32 v70, v70
	s_nop 0
	v_mul_f32_e32 v76, 0x3f317217, v70
	v_fma_f32 v76, v70, s30, -v76
	v_fmac_f32_e32 v76, 0x3377d1cf, v70
	v_fmac_f32_e32 v76, 0x3f317217, v70
	v_cmp_lt_f32_e64 s[0:1], |v70|, s19
	s_nop 1
	v_cndmask_b32_e64 v70, v70, v76, s[0:1]
	v_cndmask_b32_e32 v76, 0, v211, vcc
	v_sub_f32_e32 v70, v70, v76
	v_max_f32_e32 v76, 0, v78
	v_mul_f32_e64 v78, |v78|, s17
	v_exp_f32_e32 v78, v78
	v_pk_add_f32 v[68:69], v[68:69], v[70:71]
	v_add_f32_e32 v78, 1.0, v78
	v_cmp_gt_f32_e32 vcc, s21, v78
	s_nop 1
	v_cndmask_b32_e64 v80, 0, 32, vcc
	v_ldexp_f32 v78, v78, v80
	v_log_f32_e32 v78, v78
	s_nop 0
	v_mul_f32_e32 v80, 0x3f317217, v78
	v_fma_f32 v80, v78, s30, -v80
	v_fmac_f32_e32 v80, 0x3377d1cf, v78
	v_fmac_f32_e32 v80, 0x3f317217, v78
	v_cmp_lt_f32_e64 s[0:1], |v78|, s19
	s_nop 1
	v_cndmask_b32_e64 v78, v78, v80, s[0:1]
	v_cndmask_b32_e32 v80, 0, v211, vcc
	v_sub_f32_e32 v78, v78, v80
	v_max_f32_e32 v80, 0, v82
	v_mul_f32_e64 v82, |v82|, s17
	v_exp_f32_e32 v82, v82
	s_nop 0
	v_add_f32_e32 v82, 1.0, v82
	v_cmp_gt_f32_e32 vcc, s21, v82
	s_nop 1
	v_cndmask_b32_e64 v107, 0, 32, vcc
	v_ldexp_f32 v82, v82, v107
	v_log_f32_e32 v82, v82
	s_nop 0
	v_mul_f32_e32 v107, 0x3f317217, v82
	v_fma_f32 v107, v82, s30, -v107
	v_fmac_f32_e32 v107, 0x3377d1cf, v82
	v_fmac_f32_e32 v107, 0x3f317217, v82
	v_cmp_lt_f32_e64 s[0:1], |v82|, s19
	s_nop 1
	v_cndmask_b32_e64 v82, v82, v107, s[0:1]
	v_cndmask_b32_e32 v107, 0, v211, vcc
	v_sub_f32_e32 v82, v82, v107
	v_add_u32_e32 v107, s34, v100
	v_or_b32_e32 v70, 26, v107
	v_or_b32_e32 v109, 25, v107
	v_cmp_lt_i32_e64 s[60:61], v70, v72
	v_pk_add_f32 v[70:71], v[76:77], v[78:79]
	v_cmp_lt_i32_e64 s[58:59], v109, v72
	v_fma_f32 v109, v33, s20, -v69
	v_or_b32_e32 v33, 2, v107
	v_fma_f32 v111, v34, s20, -v71
	v_or_b32_e32 v34, 27, v107
	v_cmp_lt_i32_e64 s[44:45], v33, v73
	v_or_b32_e32 v33, 3, v107
	v_cmp_lt_i32_e64 s[62:63], v34, v72
	v_pk_add_f32 v[76:77], v[80:81], v[82:83]
	v_or_b32_e32 v34, 16, v107
	v_cmp_lt_i32_e64 s[50:51], v33, v73
	v_fma_f32 v82, v35, s20, -v77
	v_or_b32_e32 v33, 8, v107
	v_cmp_lt_i32_e32 vcc, v34, v72
	v_pk_add_f32 v[34:35], v[84:85], v[86:87]
	v_or_b32_e32 v78, 17, v107
	v_cmp_lt_i32_e64 s[48:49], v33, v73
	v_fma_f32 v33, v36, s20, -v35
	v_or_b32_e32 v36, 9, v107
	v_cmp_lt_i32_e64 s[0:1], v78, v72
	v_pk_add_f32 v[78:79], v[88:89], v[90:91]
	v_cmp_lt_i32_e64 s[52:53], v36, v73
; DI void sb_unit(const Params& P, LAS char* lds, int b, int hd, int qb, int wave, int lane) {
;     ...
;         for (int i = 0; i < 16; ++i) { const int kidx = kbase + (i & 3) + 8 * (i >> 2) + 4 * h; const bool ok = kidx < qpos; vm |= ok ? (1u << i) : 0u;
;             const float z = s[i] * 0.125f; const float sp = fmaxf(z, 0.f) + __logf(1.0f + __expf(-fabsf(z)));
;             l1m[i] = ok ? -sp : 0.f; ls[i] = z - sp; }
;         float G[4], Gp[4], tot[4];
; #pragma unroll
;         for (int g = 0; g < 4; ++g) { G[g] = (l1m[4 * g] + l1m[4 * g + 1]) + (l1m[4 * g + 2] + l1m[4 * g + 3]); Gp[g] = shx32(G[g], lane); tot[g] = G[g] + Gp[g]; }
;         float aft[4];
;         aft[3] = (h == 0) ? Gp[3] : 0.f;
;         aft[2] = tot[3] + ((h == 0) ? Gp[2] : 0.f);
;         aft[1] = tot[3] + tot[2] + ((h == 0) ? Gp[1] : 0.f);
;         aft[0] = tot[3] + tot[2] + tot[1] + ((h == 0) ? Gp[0] : 0.f);
;         float p[16];
; #pragma unroll
;         for (int g = 0; g < 4; ++g) {
;             const float base = carry + aft[g];
;             const float w3 = 0.f, w2 = l1m[4 * g + 3], w1 = w2 + l1m[4 * g + 2], w0 = w1 + l1m[4 * g + 1];
;             p[4 * g + 0] = ((vm >> (4 * g + 0)) & 1u) ? __expf(ls[4 * g + 0] + base + w0) : 0.f;
;             p[4 * g + 1] = ((vm >> (4 * g + 1)) & 1u) ? __expf(ls[4 * g + 1] + base + w1) : 0.f;
;             p[4 * g + 2] = ((vm >> (4 * g + 2)) & 1u) ? __expf(ls[4 * g + 2] + base + w2) : 0.f;
;             p[4 * g + 3] = ((vm >> (4 * g + 3)) & 1u) ? __expf(ls[4 * g + 3] + base + w3) : 0.f;
;         }
;         carry += (tot[0] + tot[1]) + (tot[2] + tot[3]);
	v_fma_f32 v85, v37, s20, -v79
	v_or_b32_e32 v36, 10, v107
	v_or_b32_e32 v37, 18, v107
	v_cmp_lt_i32_e64 s[38:39], v37, v72
	v_cmp_lt_i32_e64 s[54:55], v36, v73
	v_pk_add_f32 v[36:37], v[92:93], v[94:95]
	v_or_b32_e32 v80, 19, v107
	v_fma_f32 v87, v38, s20, -v37
	v_or_b32_e32 v38, 11, v107
	v_cmp_lt_i32_e64 s[40:41], v80, v72
	v_cmp_lt_i32_e64 s[56:57], v38, v73
	v_pk_add_f32 v[80:81], v[96:97], v[98:99]
	v_or_b32_e32 v108, 1, v107
	v_fma_f32 v89, v39, s20, -v81
	v_cndmask_b32_e64 v39, 0, -v35, s[48:49]
	v_cndmask_b32_e64 v38, 0, -v34, vcc
	v_fma_f32 v91, v40, s20, -v34
	v_cndmask_b32_e64 v35, 0, -v79, s[52:53]
	v_cndmask_b32_e64 v34, 0, -v78, s[0:1]
	v_fma_f32 v78, v41, s20, -v78
	v_cndmask_b32_e64 v41, 0, -v37, s[54:55]
	v_cndmask_b32_e64 v40, 0, -v36, s[38:39]
	v_fma_f32 v93, v42, s20, -v36
	v_cndmask_b32_e64 v37, 0, -v81, s[56:57]
	v_cndmask_b32_e64 v36, 0, -v80, s[40:41]
	v_add_u32_e32 v42, 24, v107
	v_cmp_lt_i32_e64 s[42:43], v108, v73
	v_fma_f32 v80, v43, s20, -v80
	v_cmp_lt_i32_e64 s[64:65], v107, v73
	v_cmp_lt_i32_e64 s[66:67], v42, v72
	v_pk_add_f32 v[42:43], v[64:65], v[66:67]
	v_pk_add_f32 v[38:39], v[38:39], v[34:35]
	v_pk_add_f32 v[40:41], v[40:41], v[36:37]
	v_cndmask_b32_e64 v65, 0, -v43, s[64:65]
	v_cndmask_b32_e64 v64, 0, -v42, s[66:67]
	v_fma_f32 v95, v44, s20, -v42
	v_cndmask_b32_e64 v67, 0, -v69, s[42:43]
	v_cndmask_b32_e64 v66, 0, -v68, s[58:59]
	v_fma_f32 v96, v45, s20, -v68
	v_cndmask_b32_e64 v45, 0, -v71, s[44:45]
	v_cndmask_b32_e64 v44, 0, -v70, s[60:61]
	v_cndmask_b32_e64 v69, 0, -v77, s[50:51]
	v_cndmask_b32_e64 v68, 0, -v76, s[62:63]
	v_pk_add_f32 v[38:39], v[38:39], v[40:41]
	v_fma_f32 v98, v46, s20, -v70
	v_fma_f32 v76, v47, s20, -v76
	v_pk_add_f32 v[46:47], v[64:65], v[66:67]
	v_pk_add_f32 v[44:45], v[44:45], v[68:69]
	v_mov_b32_e32 v64, v39
	v_mov_b32_e32 v65, v39
	v_mov_b32_e32 v77, v38
	v_mov_b32_e32 v107, v38
	v_pk_add_f32 v[46:47], v[46:47], v[44:45]
	v_permlane32_swap_b32_e32 v64, v65
	v_permlane32_swap_b32_e32 v77, v107
	v_mov_b32_e32 v70, v47
	v_mov_b32_e32 v71, v47
	v_cndmask_b32_e64 v65, v64, v65, s[36:37]
	v_cndmask_b32_e64 v64, v77, v107, s[36:37]
	v_mov_b32_e32 v77, v46
	v_mov_b32_e32 v107, v46
	v_cndmask_b32_e64 v84, 0, 32, s[52:53]
	v_cndmask_b32_e64 v79, 0, v199, s[38:39]
	v_cndmask_b32_e64 v94, 0, v200, s[40:41]
	v_permlane32_swap_b32_e32 v70, v71
	v_permlane32_swap_b32_e32 v77, v107
	v_cndmask_b32_e64 v112, 0, 8, s[50:51]
	v_cndmask_b32_e64 v83, 0, 16, s[48:49]
	v_cndmask_b32_e64 v71, v70, v71, s[36:37]
	v_cndmask_b32_e64 v70, v77, v107, s[36:37]
	v_or3_b32 v77, v84, v79, v94
	v_cndmask_b32_e64 v110, 0, 4, s[44:45]
	v_cndmask_b32_e64 v86, 0, 64, s[54:55]
	v_or3_b32 v77, v83, v112, v77
	v_cndmask_b32_e64 v108, 0, 2, s[42:43]
	v_cndmask_b32_e64 v88, 0, v196, s[56:57]
	v_or3_b32 v77, v110, v86, v77
	v_cndmask_b32_e32 v90, 0, v197, vcc
	v_cndmask_b32_e64 v92, 0, v198, s[0:1]
	v_or3_b32 v77, v108, v88, v77
	v_cndmask_b32_e64 v81, 0, v201, s[66:67]
	v_cndmask_b32_e64 v42, 0, v202, s[58:59]
	v_or3_b32 v77, v90, v92, v77
	v_pk_add_f32 v[38:39], v[38:39], v[64:65]
	v_pk_add_f32 v[46:47], v[46:47], v[70:71]
	v_or3_b32 v77, v81, v42, v77
	v_cndmask_b32_e64 v42, 0, v64, s[36:37]
	v_add_f32_e32 v64, v42, v46
	v_pk_add_f32 v[46:47], v[38:39], v[46:47]
	v_cndmask_b32_e64 v42, 0, v65, s[36:37]
	v_add_f32_e32 v38, v39, v46
	v_cndmask_b32_e64 v39, 0, v71, s[36:37]
	v_add_f32_e32 v38, v39, v38
	v_add_f32_e32 v65, v42, v46
	v_add_f32_e32 v39, v102, v38
	v_fma_f32 v43, v32, s20, -v43
	v_mov_b32_e32 v42, v67
	v_mov_b32_e32 v38, v45
	v_pk_add_f32 v[42:43], v[42:43], v[38:39]
	v_mov_b32_e32 v38, v41
	v_add_f32_e32 v32, v42, v43
	v_mul_f32_e32 v32, 0x3fb8aa3b, v32
	v_exp_f32_e32 v32, v32
	v_cndmask_b32_e64 v70, 0, v70, s[36:37]
	v_mov_b32_e32 v67, v95
	v_cndmask_b32_e64 v97, 0, v203, s[60:61]
	v_cndmask_b32_e64 v42, 0, v32, s[64:65]
	v_add_f32_e32 v32, v109, v39
; #define MFMA32(a, b, c) __builtin_amdgcn_mfma_f32_32x32x16_bf16((a), (b), (c), 0, 0, 0)
; DI void pv_rows(f32x16 (&o)[2], LAS const char* Vl, int row0, const bf16x8 (&pf)[2], int lane) {
;     ...
;     __builtin_amdgcn_s_setprio(1);
; #pragma unroll
;     for (int s2 = 0; s2 < 2; ++s2)
; #pragma unroll
;         for (int dt = 0; dt < 2; ++dt) o[dt] = MFMA32(vf[dt][s2], pf[s2], o[dt]);
;     __builtin_amdgcn_s_setprio(0);
; DI void sb_unit(const Params& P, LAS char* lds, int b, int hd, int qb, int wave, int lane) {
;     ...
;         for (int g = 0; g < 4; ++g) {
;             const float base = carry + aft[g];
;             const float w3 = 0.f, w2 = l1m[4 * g + 3], w1 = w2 + l1m[4 * g + 2], w0 = w1 + l1m[4 * g + 1];
;             p[4 * g + 0] = ((vm >> (4 * g + 0)) & 1u) ? __expf(ls[4 * g + 0] + base + w0) : 0.f;
;             p[4 * g + 1] = ((vm >> (4 * g + 1)) & 1u) ? __expf(ls[4 * g + 1] + base + w1) : 0.f;
;             p[4 * g + 2] = ((vm >> (4 * g + 2)) & 1u) ? __expf(ls[4 * g + 2] + base + w2) : 0.f;
;             p[4 * g + 3] = ((vm >> (4 * g + 3)) & 1u) ? __expf(ls[4 * g + 3] + base + w3) : 0.f;
;         }
;         carry += (tot[0] + tot[1]) + (tot[2] + tot[3]);
;         bf16x8 pf[2]; pack_p(p, pf);
;         pv_rows(o, Vl, 0, pf, lane);
;         asm volatile("" ::: "memory");
;         if (__builtin_amdgcn_ballot_w64(carry >= -120.0f) == 0ull) break;
	v_add_f32_e32 v32, v45, v32
	v_mul_f32_e32 v32, 0x3fb8aa3b, v32
	v_exp_f32_e32 v32, v32
	v_add_f32_e32 v45, v102, v70
	v_cndmask_b32_e64 v99, 0, v204, s[62:63]
	v_or3_b32 v79, v97, v99, v77
	v_cndmask_b32_e64 v43, 0, v32, s[42:43]
	v_add_f32_e32 v32, v111, v39
	v_add_f32_e32 v32, v69, v32
	v_mul_f32_e32 v32, 0x3fb8aa3b, v32
	v_exp_f32_e32 v32, v32
	s_nop 0
	v_cndmask_b32_e64 v69, 0, v32, s[44:45]
	v_add_f32_e32 v32, v82, v39
	v_add_f32_e32 v32, 0, v32
	v_mul_f32_e32 v32, 0x3fb8aa3b, v32
	v_exp_f32_e32 v32, v32
	v_add_f32_e32 v39, v102, v65
	v_cndmask_b32_e64 v71, 0, v32, s[50:51]
	v_mov_b32_e32 v32, v35
	v_pk_add_f32 v[32:33], v[32:33], v[38:39]
	v_mov_b32_e32 v35, v91
	v_add_f32_e32 v32, v32, v33
	v_mul_f32_e32 v32, 0x3fb8aa3b, v32
	v_exp_f32_e32 v32, v32
	s_nop 0
	v_cndmask_b32_e64 v38, 0, v32, s[48:49]
	v_add_f32_e32 v32, v85, v39
	v_add_f32_e32 v32, v41, v32
	v_mul_f32_e32 v32, 0x3fb8aa3b, v32
	v_exp_f32_e32 v32, v32
	v_add_f32_e32 v41, v102, v64
	v_cndmask_b32_e64 v65, 0, v32, s[52:53]
	v_add_f32_e32 v32, v87, v39
	v_add_f32_e32 v32, v37, v32
	v_mul_f32_e32 v32, 0x3fb8aa3b, v32
	v_exp_f32_e32 v32, v32
	v_cvt_pk_bf16_f32 v37, v69, v71
	v_cvt_pk_bf16_f32 v38, v38, v65
	v_cndmask_b32_e64 v81, 0, v32, s[54:55]
	v_add_f32_e32 v32, v89, v39
	v_add_f32_e32 v32, 0, v32
	v_mul_f32_e32 v32, 0x3fb8aa3b, v32
	v_exp_f32_e32 v32, v32
	s_nop 0
	v_cndmask_b32_e64 v39, 0, v32, s[56:57]
	v_pk_add_f32 v[32:33], v[34:35], v[40:41]
	v_cvt_pk_bf16_f32 v39, v81, v39
	v_add_f32_e32 v32, v32, v33
	v_mul_f32_e32 v32, 0x3fb8aa3b, v32
	v_exp_f32_e32 v32, v32
	s_nop 0
	v_cndmask_b32_e32 v34, 0, v32, vcc
	v_add_f32_e32 v32, v78, v41
	v_add_f32_e32 v32, v40, v32
	v_mul_f32_e32 v32, 0x3fb8aa3b, v32
	v_exp_f32_e32 v32, v32
	s_nop 0
	v_cndmask_b32_e64 v35, 0, v32, s[0:1]
	v_add_f32_e32 v32, v93, v41
	v_add_f32_e32 v32, v36, v32
	v_mul_f32_e32 v32, 0x3fb8aa3b, v32
	v_exp_f32_e32 v32, v32
	v_cvt_pk_bf16_f32 v36, v42, v43
	v_cndmask_b32_e64 v40, 0, v32, s[38:39]
	v_add_f32_e32 v32, v80, v41
	v_add_f32_e32 v32, 0, v32
	v_mul_f32_e32 v32, 0x3fb8aa3b, v32
	v_exp_f32_e32 v32, v32
	s_nop 0
	v_cndmask_b32_e64 v41, 0, v32, s[40:41]
	v_pk_add_f32 v[32:33], v[66:67], v[44:45]
	s_nop 0
	v_add_f32_e32 v32, v32, v33
	v_mul_f32_e32 v32, 0x3fb8aa3b, v32
	v_exp_f32_e32 v32, v32
	v_and_b32_e32 v33, 0x1000, v77
	v_cmp_ne_u32_e32 vcc, 0, v33
	v_and_b32_e32 v33, 0x2000, v77
	s_nop 0
	v_cndmask_b32_e32 v64, 0, v32, vcc
	v_add_f32_e32 v32, v96, v45
	v_add_f32_e32 v32, v44, v32
	v_mul_f32_e32 v32, 0x3fb8aa3b, v32
	v_exp_f32_e32 v32, v32
	v_cmp_ne_u32_e32 vcc, 0, v33
	v_and_b32_e32 v33, 0x4000, v79
	s_nop 0
	v_cndmask_b32_e32 v44, 0, v32, vcc
	v_add_f32_e32 v32, v98, v45
	v_add_f32_e32 v32, v68, v32
	v_mul_f32_e32 v32, 0x3fb8aa3b, v32
	v_exp_f32_e32 v32, v32
	v_cmp_ne_u32_e32 vcc, 0, v33
	v_and_b32_e32 v33, 0x8000, v79
	s_nop 0
	v_cndmask_b32_e32 v66, 0, v32, vcc
	v_add_f32_e32 v32, v76, v45
	v_add_f32_e32 v32, 0, v32
	v_mul_f32_e32 v32, 0x3fb8aa3b, v32
	v_exp_f32_e32 v32, v32
	v_cmp_ne_u32_e32 vcc, 0, v33
	v_cvt_pk_bf16_f32 v33, v40, v41
	s_nop 0
	v_cndmask_b32_e32 v45, 0, v32, vcc
	v_add_f32_e32 v32, v46, v47
	v_add_f32_e32 v102, v102, v32
	v_cvt_pk_bf16_f32 v32, v34, v35
	v_cvt_pk_bf16_f32 v34, v64, v44
	v_cvt_pk_bf16_f32 v35, v66, v45
	s_setprio 1
	s_waitcnt lgkmcnt(0)
	v_mfma_f32_32x32x16_bf16 v[16:31], v[116:119], v[36:39], v[16:31]
	v_mfma_f32_32x32x16_bf16 v[0:15], v[120:123], v[36:39], v[0:15]
	v_mfma_f32_32x32x16_bf16 v[16:31], v[124:127], v[32:35], v[16:31]
	v_mfma_f32_32x32x16_bf16 v[0:15], v[160:163], v[32:35], v[0:15]
	s_setprio 0
	s_mov_b32 s0, 0xc2f00000
	v_cmp_le_f32_e32 vcc, s0, v102
	s_cmp_lg_u64 vcc, 0
	s_cselect_b64 s[0:1], -1, 0
	v_add_co_u32_e32 v103, vcc, -1, v103
	s_and_b64 s[0:1], vcc, s[0:1]
	s_sub_i32 s34, s34, 32
	s_and_b64 vcc, exec, s[0:1]
	s_cbranch_vccnz .LBB0_940
	v_mov_b32_e32 v168, v100
	s_branch .LBB0_933
